# phase 0 adaLN GEMV: 36 silu loads issued together; K loop with a 32-deep ring of weight loads and LDS operands one group ahead
# speedup vs baseline: 1.0425x; 1.0037x over previous
; DEV float sigm(float x) { return __builtin_amdgcn_rcpf(1.0f + __builtin_amdgcn_exp2f(x * -1.4426950408889634f)); }
; DEV void ph_ada(const P& p, char* smem) {
;     ...
;     for (int i = tid; i < 9 * 1024; i += 256) { const int bi = i >> 10, k = i & 1023; const float v = bi < 8 ? p.c[bi * 1024 + k] : p.c_ctx[k]; sc[i] = v * sigm(v); }
.LBB0_12:
	s_andn2_b64 vcc, exec, s[4:5]
	s_cbranch_vccnz .LBB0_24
	s_load_dwordx4 s[4:7], s[14:15], 0x18
	s_load_dwordx2 s[12:13], s[14:15], 0x28
	v_readfirstlane_b32 s16, v201
	s_lshr_b32 s21, s16, 8
	s_mul_i32 s21, s21, 0x14000
	s_movk_i32 s16, 0x2400
	v_cmp_gt_i32_e32 vcc, s16, v2
	v_lshl_add_u32 v10, v2, 2, s21
	s_and_saveexec_b64 s[16:17], vcc
	s_cbranch_execz .LBB0_16
	s_load_dwordx2 s[18:19], s[14:15], 0x8
	v_lshlrev_b32_e32 v76, 2, v2
	v_mov_b32_e32 v5, 0
	s_waitcnt lgkmcnt(0)
	s_mov_b64 s[22:23], s[18:19]
	global_load_dword v80, v76, s[22:23]
	s_add_u32 s22, s22, 0x400
	s_addc_u32 s23, s23, 0
	global_load_dword v81, v76, s[22:23]
	s_add_u32 s22, s22, 0x400
	s_addc_u32 s23, s23, 0
	global_load_dword v82, v76, s[22:23]
	s_add_u32 s22, s22, 0x400
	s_addc_u32 s23, s23, 0
	global_load_dword v83, v76, s[22:23]
	s_add_u32 s22, s22, 0x400
	s_addc_u32 s23, s23, 0
	global_load_dword v84, v76, s[22:23]
	s_add_u32 s22, s22, 0x400
	s_addc_u32 s23, s23, 0
	global_load_dword v85, v76, s[22:23]
	s_add_u32 s22, s22, 0x400
	s_addc_u32 s23, s23, 0
	global_load_dword v86, v76, s[22:23]
	s_add_u32 s22, s22, 0x400
	s_addc_u32 s23, s23, 0
	global_load_dword v87, v76, s[22:23]
	s_add_u32 s22, s22, 0x400
	s_addc_u32 s23, s23, 0
	global_load_dword v88, v76, s[22:23]
	s_add_u32 s22, s22, 0x400
	s_addc_u32 s23, s23, 0
	global_load_dword v89, v76, s[22:23]
	s_add_u32 s22, s22, 0x400
	s_addc_u32 s23, s23, 0
	global_load_dword v90, v76, s[22:23]
	s_add_u32 s22, s22, 0x400
	s_addc_u32 s23, s23, 0
	global_load_dword v91, v76, s[22:23]
	s_add_u32 s22, s22, 0x400
	s_addc_u32 s23, s23, 0
	global_load_dword v92, v76, s[22:23]
	s_add_u32 s22, s22, 0x400
	s_addc_u32 s23, s23, 0
	global_load_dword v93, v76, s[22:23]
	s_add_u32 s22, s22, 0x400
	s_addc_u32 s23, s23, 0
	global_load_dword v94, v76, s[22:23]
	s_add_u32 s22, s22, 0x400
	s_addc_u32 s23, s23, 0
	global_load_dword v95, v76, s[22:23]
	s_add_u32 s22, s22, 0x400
	s_addc_u32 s23, s23, 0
	global_load_dword v96, v76, s[22:23]
	s_add_u32 s22, s22, 0x400
	s_addc_u32 s23, s23, 0
	global_load_dword v97, v76, s[22:23]
	s_add_u32 s22, s22, 0x400
	s_addc_u32 s23, s23, 0
	global_load_dword v98, v76, s[22:23]
	s_add_u32 s22, s22, 0x400
	s_addc_u32 s23, s23, 0
	global_load_dword v99, v76, s[22:23]
	s_add_u32 s22, s22, 0x400
	s_addc_u32 s23, s23, 0
	global_load_dword v100, v76, s[22:23]
	s_add_u32 s22, s22, 0x400
	s_addc_u32 s23, s23, 0
	global_load_dword v101, v76, s[22:23]
	s_add_u32 s22, s22, 0x400
	s_addc_u32 s23, s23, 0
	global_load_dword v102, v76, s[22:23]
	s_add_u32 s22, s22, 0x400
	s_addc_u32 s23, s23, 0
	global_load_dword v103, v76, s[22:23]
	s_add_u32 s22, s22, 0x400
	s_addc_u32 s23, s23, 0
	global_load_dword v104, v76, s[22:23]
	s_add_u32 s22, s22, 0x400
	s_addc_u32 s23, s23, 0
	global_load_dword v105, v76, s[22:23]
	s_add_u32 s22, s22, 0x400
	s_addc_u32 s23, s23, 0
	global_load_dword v106, v76, s[22:23]
	s_add_u32 s22, s22, 0x400
	s_addc_u32 s23, s23, 0
	global_load_dword v107, v76, s[22:23]
	s_add_u32 s22, s22, 0x400
	s_addc_u32 s23, s23, 0
	global_load_dword v108, v76, s[22:23]
	s_add_u32 s22, s22, 0x400
	s_addc_u32 s23, s23, 0
	global_load_dword v109, v76, s[22:23]
	s_add_u32 s22, s22, 0x400
	s_addc_u32 s23, s23, 0
	global_load_dword v110, v76, s[22:23]
	s_add_u32 s22, s22, 0x400
	s_addc_u32 s23, s23, 0
	global_load_dword v111, v76, s[22:23]
	s_add_u32 s22, s22, 0x400
	s_addc_u32 s23, s23, 0
	global_load_dword v112, v76, s[4:5] offset:0
	global_load_dword v113, v76, s[4:5] offset:1024
	global_load_dword v114, v76, s[4:5] offset:2048
	global_load_dword v115, v76, s[4:5] offset:3072
	s_waitcnt vmcnt(34)
	v_mul_f32_e32 v120, 0xbfb8aa3b, v80
	v_mul_f32_e32 v121, 0xbfb8aa3b, v81
	v_exp_f32_e32 v120, v120
	v_exp_f32_e32 v121, v121
	s_nop 0
	v_add_f32_e32 v120, 1.0, v120
	v_add_f32_e32 v121, 1.0, v121
	v_rcp_f32_e32 v120, v120
	v_rcp_f32_e32 v121, v121
	s_nop 0
	v_mul_f32_e32 v80, v80, v120
	v_mul_f32_e32 v81, v81, v121
	ds_write_b32 v10, v80 offset:0
	ds_write_b32 v10, v81 offset:1024
	s_waitcnt vmcnt(32)
	v_mul_f32_e32 v120, 0xbfb8aa3b, v82
	v_mul_f32_e32 v121, 0xbfb8aa3b, v83
	v_exp_f32_e32 v120, v120
	v_exp_f32_e32 v121, v121
	s_nop 0
	v_add_f32_e32 v120, 1.0, v120
	v_add_f32_e32 v121, 1.0, v121
	v_rcp_f32_e32 v120, v120
	v_rcp_f32_e32 v121, v121
	s_nop 0
	v_mul_f32_e32 v82, v82, v120
	v_mul_f32_e32 v83, v83, v121
	ds_write_b32 v10, v82 offset:2048
	ds_write_b32 v10, v83 offset:3072
	s_waitcnt vmcnt(30)
	v_mul_f32_e32 v120, 0xbfb8aa3b, v84
	v_mul_f32_e32 v121, 0xbfb8aa3b, v85
	v_exp_f32_e32 v120, v120
	v_exp_f32_e32 v121, v121
	s_nop 0
	v_add_f32_e32 v120, 1.0, v120
	v_add_f32_e32 v121, 1.0, v121
	v_rcp_f32_e32 v120, v120
	v_rcp_f32_e32 v121, v121
	s_nop 0
	v_mul_f32_e32 v84, v84, v120
	v_mul_f32_e32 v85, v85, v121
	ds_write_b32 v10, v84 offset:4096
	ds_write_b32 v10, v85 offset:5120
	s_waitcnt vmcnt(28)
	v_mul_f32_e32 v120, 0xbfb8aa3b, v86
	v_mul_f32_e32 v121, 0xbfb8aa3b, v87
	v_exp_f32_e32 v120, v120
	v_exp_f32_e32 v121, v121
	s_nop 0
	v_add_f32_e32 v120, 1.0, v120
	v_add_f32_e32 v121, 1.0, v121
	v_rcp_f32_e32 v120, v120
	v_rcp_f32_e32 v121, v121
	s_nop 0
	v_mul_f32_e32 v86, v86, v120
	v_mul_f32_e32 v87, v87, v121
	ds_write_b32 v10, v86 offset:6144
	ds_write_b32 v10, v87 offset:7168
	s_waitcnt vmcnt(26)
	v_mul_f32_e32 v120, 0xbfb8aa3b, v88
	v_mul_f32_e32 v121, 0xbfb8aa3b, v89
	v_exp_f32_e32 v120, v120
	v_exp_f32_e32 v121, v121
	s_nop 0
	v_add_f32_e32 v120, 1.0, v120
	v_add_f32_e32 v121, 1.0, v121
	v_rcp_f32_e32 v120, v120
	v_rcp_f32_e32 v121, v121
	s_nop 0
	v_mul_f32_e32 v88, v88, v120
	v_mul_f32_e32 v89, v89, v121
	ds_write_b32 v10, v88 offset:8192
	ds_write_b32 v10, v89 offset:9216
	s_waitcnt vmcnt(24)
; DEV float sigm(float x) { return __builtin_amdgcn_rcpf(1.0f + __builtin_amdgcn_exp2f(x * -1.4426950408889634f)); }
; DEV void ph_ada(const P& p, char* smem) {
;     ...
;     for (int i = tid; i < 9 * 1024; i += 256) { const int bi = i >> 10, k = i & 1023; const float v = bi < 8 ? p.c[bi * 1024 + k] : p.c_ctx[k]; sc[i] = v * sigm(v); }
	v_mul_f32_e32 v120, 0xbfb8aa3b, v90
	v_mul_f32_e32 v121, 0xbfb8aa3b, v91
	v_exp_f32_e32 v120, v120
	v_exp_f32_e32 v121, v121
	s_nop 0
	v_add_f32_e32 v120, 1.0, v120
	v_add_f32_e32 v121, 1.0, v121
	v_rcp_f32_e32 v120, v120
	v_rcp_f32_e32 v121, v121
	s_nop 0
	v_mul_f32_e32 v90, v90, v120
	v_mul_f32_e32 v91, v91, v121
	ds_write_b32 v10, v90 offset:10240
	ds_write_b32 v10, v91 offset:11264
	s_waitcnt vmcnt(22)
	v_mul_f32_e32 v120, 0xbfb8aa3b, v92
	v_mul_f32_e32 v121, 0xbfb8aa3b, v93
	v_exp_f32_e32 v120, v120
	v_exp_f32_e32 v121, v121
	s_nop 0
	v_add_f32_e32 v120, 1.0, v120
	v_add_f32_e32 v121, 1.0, v121
	v_rcp_f32_e32 v120, v120
	v_rcp_f32_e32 v121, v121
	s_nop 0
	v_mul_f32_e32 v92, v92, v120
	v_mul_f32_e32 v93, v93, v121
	ds_write_b32 v10, v92 offset:12288
	ds_write_b32 v10, v93 offset:13312
	s_waitcnt vmcnt(20)
	v_mul_f32_e32 v120, 0xbfb8aa3b, v94
	v_mul_f32_e32 v121, 0xbfb8aa3b, v95
	v_exp_f32_e32 v120, v120
	v_exp_f32_e32 v121, v121
	s_nop 0
	v_add_f32_e32 v120, 1.0, v120
	v_add_f32_e32 v121, 1.0, v121
	v_rcp_f32_e32 v120, v120
	v_rcp_f32_e32 v121, v121
	s_nop 0
	v_mul_f32_e32 v94, v94, v120
	v_mul_f32_e32 v95, v95, v121
	ds_write_b32 v10, v94 offset:14336
	ds_write_b32 v10, v95 offset:15360
	s_waitcnt vmcnt(18)
	v_mul_f32_e32 v120, 0xbfb8aa3b, v96
	v_mul_f32_e32 v121, 0xbfb8aa3b, v97
	v_exp_f32_e32 v120, v120
	v_exp_f32_e32 v121, v121
	s_nop 0
	v_add_f32_e32 v120, 1.0, v120
	v_add_f32_e32 v121, 1.0, v121
	v_rcp_f32_e32 v120, v120
	v_rcp_f32_e32 v121, v121
	s_nop 0
	v_mul_f32_e32 v96, v96, v120
	v_mul_f32_e32 v97, v97, v121
	ds_write_b32 v10, v96 offset:16384
	ds_write_b32 v10, v97 offset:17408
	s_waitcnt vmcnt(16)
	v_mul_f32_e32 v120, 0xbfb8aa3b, v98
	v_mul_f32_e32 v121, 0xbfb8aa3b, v99
	v_exp_f32_e32 v120, v120
	v_exp_f32_e32 v121, v121
	s_nop 0
	v_add_f32_e32 v120, 1.0, v120
	v_add_f32_e32 v121, 1.0, v121
	v_rcp_f32_e32 v120, v120
	v_rcp_f32_e32 v121, v121
	s_nop 0
	v_mul_f32_e32 v98, v98, v120
	v_mul_f32_e32 v99, v99, v121
	ds_write_b32 v10, v98 offset:18432
	ds_write_b32 v10, v99 offset:19456
	s_waitcnt vmcnt(14)
	v_mul_f32_e32 v120, 0xbfb8aa3b, v100
	v_mul_f32_e32 v121, 0xbfb8aa3b, v101
	v_exp_f32_e32 v120, v120
	v_exp_f32_e32 v121, v121
	s_nop 0
	v_add_f32_e32 v120, 1.0, v120
	v_add_f32_e32 v121, 1.0, v121
	v_rcp_f32_e32 v120, v120
	v_rcp_f32_e32 v121, v121
	s_nop 0
	v_mul_f32_e32 v100, v100, v120
	v_mul_f32_e32 v101, v101, v121
	ds_write_b32 v10, v100 offset:20480
	ds_write_b32 v10, v101 offset:21504
	s_waitcnt vmcnt(12)
	v_mul_f32_e32 v120, 0xbfb8aa3b, v102
	v_mul_f32_e32 v121, 0xbfb8aa3b, v103
	v_exp_f32_e32 v120, v120
	v_exp_f32_e32 v121, v121
	s_nop 0
	v_add_f32_e32 v120, 1.0, v120
	v_add_f32_e32 v121, 1.0, v121
	v_rcp_f32_e32 v120, v120
	v_rcp_f32_e32 v121, v121
	s_nop 0
	v_mul_f32_e32 v102, v102, v120
	v_mul_f32_e32 v103, v103, v121
	ds_write_b32 v10, v102 offset:22528
	ds_write_b32 v10, v103 offset:23552
	s_waitcnt vmcnt(10)
	v_mul_f32_e32 v120, 0xbfb8aa3b, v104
	v_mul_f32_e32 v121, 0xbfb8aa3b, v105
	v_exp_f32_e32 v120, v120
	v_exp_f32_e32 v121, v121
	s_nop 0
	v_add_f32_e32 v120, 1.0, v120
	v_add_f32_e32 v121, 1.0, v121
	v_rcp_f32_e32 v120, v120
	v_rcp_f32_e32 v121, v121
	s_nop 0
	v_mul_f32_e32 v104, v104, v120
	v_mul_f32_e32 v105, v105, v121
	ds_write_b32 v10, v104 offset:24576
	ds_write_b32 v10, v105 offset:25600
	s_waitcnt vmcnt(8)
	v_mul_f32_e32 v120, 0xbfb8aa3b, v106
	v_mul_f32_e32 v121, 0xbfb8aa3b, v107
	v_exp_f32_e32 v120, v120
	v_exp_f32_e32 v121, v121
	s_nop 0
	v_add_f32_e32 v120, 1.0, v120
	v_add_f32_e32 v121, 1.0, v121
	v_rcp_f32_e32 v120, v120
	v_rcp_f32_e32 v121, v121
	s_nop 0
	v_mul_f32_e32 v106, v106, v120
	v_mul_f32_e32 v107, v107, v121
	ds_write_b32 v10, v106 offset:26624
	ds_write_b32 v10, v107 offset:27648
	s_waitcnt vmcnt(6)
	v_mul_f32_e32 v120, 0xbfb8aa3b, v108
	v_mul_f32_e32 v121, 0xbfb8aa3b, v109
	v_exp_f32_e32 v120, v120
	v_exp_f32_e32 v121, v121
	s_nop 0
	v_add_f32_e32 v120, 1.0, v120
	v_add_f32_e32 v121, 1.0, v121
	v_rcp_f32_e32 v120, v120
	v_rcp_f32_e32 v121, v121
	s_nop 0
	v_mul_f32_e32 v108, v108, v120
	v_mul_f32_e32 v109, v109, v121
	ds_write_b32 v10, v108 offset:28672
	ds_write_b32 v10, v109 offset:29696
	s_waitcnt vmcnt(4)
	v_mul_f32_e32 v120, 0xbfb8aa3b, v110
	v_mul_f32_e32 v121, 0xbfb8aa3b, v111
	v_exp_f32_e32 v120, v120
	v_exp_f32_e32 v121, v121
	s_nop 0
	v_add_f32_e32 v120, 1.0, v120
	v_add_f32_e32 v121, 1.0, v121
	v_rcp_f32_e32 v120, v120
	v_rcp_f32_e32 v121, v121
	s_nop 0
	v_mul_f32_e32 v110, v110, v120
	v_mul_f32_e32 v111, v111, v121
	ds_write_b32 v10, v110 offset:30720
	ds_write_b32 v10, v111 offset:31744
	s_waitcnt vmcnt(2)
	v_mul_f32_e32 v120, 0xbfb8aa3b, v112
	v_mul_f32_e32 v121, 0xbfb8aa3b, v113
	v_exp_f32_e32 v120, v120
	v_exp_f32_e32 v121, v121
	s_nop 0
	v_add_f32_e32 v120, 1.0, v120
	v_add_f32_e32 v121, 1.0, v121
	v_rcp_f32_e32 v120, v120
	v_rcp_f32_e32 v121, v121
	s_nop 0
	v_mul_f32_e32 v112, v112, v120
	v_mul_f32_e32 v113, v113, v121
	ds_write_b32 v10, v112 offset:32768
	ds_write_b32 v10, v113 offset:33792
	s_waitcnt vmcnt(0)
	v_mul_f32_e32 v120, 0xbfb8aa3b, v114
	v_mul_f32_e32 v121, 0xbfb8aa3b, v115
	v_exp_f32_e32 v120, v120
	v_exp_f32_e32 v121, v121
	s_nop 0
	v_add_f32_e32 v120, 1.0, v120
	v_add_f32_e32 v121, 1.0, v121
	v_rcp_f32_e32 v120, v120
	v_rcp_f32_e32 v121, v121
	s_nop 0
	v_mul_f32_e32 v114, v114, v120
	v_mul_f32_e32 v115, v115, v121
	ds_write_b32 v10, v114 offset:34816
	ds_write_b32 v10, v115 offset:35840

; DEV int vbid() { return (int)blockIdx.x * 2 + vbsel(); }
; DEV int vgrid() { return (int)gridDim.x * 2; }
; DEV void ph_ada(const P& p, char* smem) {
;     ...
;     for (int item = vbid(); item < 192; item += vgrid()) {
;       const int l = item / 96, n0 = (item % 96) * 64, nn = tid & 63, kq = tid >> 6;
;       float acc[9];
; #pragma unroll
;       for (int b = 0; b < 9; ++b) acc[b] = 0.f;
;       const float* w = p.ada_w + (size_t)l * 1024 * 6144 + n0 + nn;
;       for (int k = kq * 256; k < kq * 256 + 256; ++k) {
;         const float wv = w[(size_t)k * 6144];
; #pragma unroll
;         for (int b = 0; b < 9; ++b) acc[b] += sc[b * 1024 + k] * wv;
;       }
.LBB0_19:
	s_mul_hi_i32 s2, s16, 0x2aaaaaab
	s_lshr_b32 s3, s2, 31
	s_ashr_i32 s2, s2, 4
	s_add_i32 s14, s2, s3
	s_mul_i32 s2, s14, 0x60
	s_sub_i32 s2, s16, s2
	s_lshl_b32 s2, s2, 6
	s_ashr_i32 s3, s2, 31
	s_mul_i32 s7, s14, 0x1800000
	s_lshl_b64 s[4:5], s[2:3], 2
	s_mul_hi_i32 s6, s14, 0x1800000
	s_add_u32 s4, s7, s4
	s_addc_u32 s5, s6, s5
	v_lshl_add_u64 v[10:11], v[8:9], 0, s[4:5]
	s_mov_b64 s[6:7], 0
	v_mov_b32_e32 v22, v4
	v_mov_b32_e32 v12, 0
	v_mov_b32_e32 v13, v5
	v_mov_b32_e32 v14, 0
	v_mov_b32_e32 v15, v5
	v_mov_b32_e32 v16, 0
	v_mov_b32_e32 v17, v5
	v_mov_b32_e32 v18, 0
	v_mov_b32_e32 v19, v5
	v_mov_b32_e32 v23, 0
	v_lshl_add_u64 v[76:77], v[10:11], 0, s[6:7]
	global_load_dword v80, v[76:77], off
	s_add_u32 s6, s6, 0x6000
	s_addc_u32 s7, s7, 0
	v_lshl_add_u64 v[76:77], v[10:11], 0, s[6:7]
	global_load_dword v81, v[76:77], off
	s_add_u32 s6, s6, 0x6000
	s_addc_u32 s7, s7, 0
	v_lshl_add_u64 v[76:77], v[10:11], 0, s[6:7]
	global_load_dword v82, v[76:77], off
	s_add_u32 s6, s6, 0x6000
	s_addc_u32 s7, s7, 0
	v_lshl_add_u64 v[76:77], v[10:11], 0, s[6:7]
	global_load_dword v83, v[76:77], off
	s_add_u32 s6, s6, 0x6000
	s_addc_u32 s7, s7, 0
	v_lshl_add_u64 v[76:77], v[10:11], 0, s[6:7]
	global_load_dword v84, v[76:77], off
	s_add_u32 s6, s6, 0x6000
	s_addc_u32 s7, s7, 0
	v_lshl_add_u64 v[76:77], v[10:11], 0, s[6:7]
	global_load_dword v85, v[76:77], off
	s_add_u32 s6, s6, 0x6000
	s_addc_u32 s7, s7, 0
	v_lshl_add_u64 v[76:77], v[10:11], 0, s[6:7]
	global_load_dword v86, v[76:77], off
	s_add_u32 s6, s6, 0x6000
	s_addc_u32 s7, s7, 0
	v_lshl_add_u64 v[76:77], v[10:11], 0, s[6:7]
	global_load_dword v87, v[76:77], off
	s_add_u32 s6, s6, 0x6000
	s_addc_u32 s7, s7, 0
	v_lshl_add_u64 v[76:77], v[10:11], 0, s[6:7]
	global_load_dword v88, v[76:77], off
	s_add_u32 s6, s6, 0x6000
	s_addc_u32 s7, s7, 0
	v_lshl_add_u64 v[76:77], v[10:11], 0, s[6:7]
	global_load_dword v89, v[76:77], off
	s_add_u32 s6, s6, 0x6000
	s_addc_u32 s7, s7, 0
	v_lshl_add_u64 v[76:77], v[10:11], 0, s[6:7]
	global_load_dword v90, v[76:77], off
	s_add_u32 s6, s6, 0x6000
	s_addc_u32 s7, s7, 0
	v_lshl_add_u64 v[76:77], v[10:11], 0, s[6:7]
	global_load_dword v91, v[76:77], off
	s_add_u32 s6, s6, 0x6000
	s_addc_u32 s7, s7, 0
	v_lshl_add_u64 v[76:77], v[10:11], 0, s[6:7]
	global_load_dword v92, v[76:77], off
	s_add_u32 s6, s6, 0x6000
	s_addc_u32 s7, s7, 0
	v_lshl_add_u64 v[76:77], v[10:11], 0, s[6:7]
	global_load_dword v93, v[76:77], off
	s_add_u32 s6, s6, 0x6000
	s_addc_u32 s7, s7, 0
	v_lshl_add_u64 v[76:77], v[10:11], 0, s[6:7]
	global_load_dword v94, v[76:77], off
	s_add_u32 s6, s6, 0x6000
	s_addc_u32 s7, s7, 0
	v_lshl_add_u64 v[76:77], v[10:11], 0, s[6:7]
	global_load_dword v95, v[76:77], off
	s_add_u32 s6, s6, 0x6000
	s_addc_u32 s7, s7, 0
	v_lshl_add_u64 v[76:77], v[10:11], 0, s[6:7]
	global_load_dword v96, v[76:77], off
	s_add_u32 s6, s6, 0x6000
	s_addc_u32 s7, s7, 0
	v_lshl_add_u64 v[76:77], v[10:11], 0, s[6:7]
	global_load_dword v97, v[76:77], off
	s_add_u32 s6, s6, 0x6000
	s_addc_u32 s7, s7, 0
	v_lshl_add_u64 v[76:77], v[10:11], 0, s[6:7]
	global_load_dword v98, v[76:77], off
	s_add_u32 s6, s6, 0x6000
	s_addc_u32 s7, s7, 0
	v_lshl_add_u64 v[76:77], v[10:11], 0, s[6:7]
	global_load_dword v99, v[76:77], off
	s_add_u32 s6, s6, 0x6000
	s_addc_u32 s7, s7, 0
	v_lshl_add_u64 v[76:77], v[10:11], 0, s[6:7]
	global_load_dword v100, v[76:77], off
	s_add_u32 s6, s6, 0x6000
	s_addc_u32 s7, s7, 0
	v_lshl_add_u64 v[76:77], v[10:11], 0, s[6:7]
	global_load_dword v101, v[76:77], off
	s_add_u32 s6, s6, 0x6000
	s_addc_u32 s7, s7, 0
	v_lshl_add_u64 v[76:77], v[10:11], 0, s[6:7]
	global_load_dword v102, v[76:77], off
	s_add_u32 s6, s6, 0x6000
	s_addc_u32 s7, s7, 0
	v_lshl_add_u64 v[76:77], v[10:11], 0, s[6:7]
	global_load_dword v103, v[76:77], off
	s_add_u32 s6, s6, 0x6000
	s_addc_u32 s7, s7, 0
	v_lshl_add_u64 v[76:77], v[10:11], 0, s[6:7]
	global_load_dword v104, v[76:77], off
	s_add_u32 s6, s6, 0x6000
	s_addc_u32 s7, s7, 0
	v_lshl_add_u64 v[76:77], v[10:11], 0, s[6:7]
	global_load_dword v105, v[76:77], off
	s_add_u32 s6, s6, 0x6000
	s_addc_u32 s7, s7, 0
	v_lshl_add_u64 v[76:77], v[10:11], 0, s[6:7]
	global_load_dword v106, v[76:77], off
	s_add_u32 s6, s6, 0x6000
	s_addc_u32 s7, s7, 0
	v_lshl_add_u64 v[76:77], v[10:11], 0, s[6:7]
	global_load_dword v107, v[76:77], off
	s_add_u32 s6, s6, 0x6000
	s_addc_u32 s7, s7, 0
	v_lshl_add_u64 v[76:77], v[10:11], 0, s[6:7]
	global_load_dword v108, v[76:77], off
	s_add_u32 s6, s6, 0x6000
	s_addc_u32 s7, s7, 0
	v_lshl_add_u64 v[76:77], v[10:11], 0, s[6:7]
	global_load_dword v109, v[76:77], off
	s_add_u32 s6, s6, 0x6000
	s_addc_u32 s7, s7, 0
	v_lshl_add_u64 v[76:77], v[10:11], 0, s[6:7]
	global_load_dword v110, v[76:77], off
	s_add_u32 s6, s6, 0x6000
	s_addc_u32 s7, s7, 0
	v_lshl_add_u64 v[76:77], v[10:11], 0, s[6:7]
	global_load_dword v111, v[76:77], off
	s_add_u32 s6, s6, 0x6000
	s_addc_u32 s7, s7, 0
	ds_read_b128 v[24:27], v22 offset:0
	ds_read_b128 v[28:31], v22 offset:4096
	ds_read_b128 v[32:35], v22 offset:8192
	ds_read_b128 v[36:39], v22 offset:12288
	ds_read_b128 v[40:43], v22 offset:16384
	ds_read_b128 v[44:47], v22 offset:20480
	ds_read_b128 v[48:51], v22 offset:24576
	ds_read_b128 v[52:55], v22 offset:28672
	ds_read_b128 v[56:59], v22 offset:32768
	s_movk_i32 s4, 7
; DEV void ph_ada(const P& p, char* smem) {
;     ...
;       for (int k = kq * 256; k < kq * 256 + 256; ++k) {
;         const float wv = w[(size_t)k * 6144];
; #pragma unroll
;         for (int b = 0; b < 9; ++b) acc[b] += sc[b * 1024 + k] * wv;
;       }
.Lada_loop:
	ds_read_b128 v[144:147], v22 offset:16
	ds_read_b128 v[148:151], v22 offset:4112
	ds_read_b128 v[152:155], v22 offset:8208
	ds_read_b128 v[156:159], v22 offset:12304
	ds_read_b128 v[160:163], v22 offset:16400
	ds_read_b128 v[164:167], v22 offset:20496
	ds_read_b128 v[168:171], v22 offset:24592
	ds_read_b128 v[172:175], v22 offset:28688
	ds_read_b128 v[176:179], v22 offset:32784
	s_waitcnt vmcnt(28) lgkmcnt(9)
	v_fmac_f32_e32 v12, v80, v24
	v_fmac_f32_e32 v13, v80, v28
	v_fmac_f32_e32 v14, v80, v32
	v_fmac_f32_e32 v15, v80, v36
	v_fmac_f32_e32 v16, v80, v40
	v_fmac_f32_e32 v17, v80, v44
	v_fmac_f32_e32 v18, v80, v48
	v_fmac_f32_e32 v19, v80, v52
	v_fmac_f32_e32 v23, v80, v56
	v_fmac_f32_e32 v12, v81, v25
	v_fmac_f32_e32 v13, v81, v29
	v_fmac_f32_e32 v14, v81, v33
	v_fmac_f32_e32 v15, v81, v37
	v_fmac_f32_e32 v16, v81, v41
	v_fmac_f32_e32 v17, v81, v45
	v_fmac_f32_e32 v18, v81, v49
	v_fmac_f32_e32 v19, v81, v53
	v_fmac_f32_e32 v23, v81, v57
	v_fmac_f32_e32 v12, v82, v26
	v_fmac_f32_e32 v13, v82, v30
	v_fmac_f32_e32 v14, v82, v34
	v_fmac_f32_e32 v15, v82, v38
	v_fmac_f32_e32 v16, v82, v42
	v_fmac_f32_e32 v17, v82, v46
	v_fmac_f32_e32 v18, v82, v50
	v_fmac_f32_e32 v19, v82, v54
	v_fmac_f32_e32 v23, v82, v58
	v_fmac_f32_e32 v12, v83, v27
	v_fmac_f32_e32 v13, v83, v31
	v_fmac_f32_e32 v14, v83, v35
	v_fmac_f32_e32 v15, v83, v39
	v_fmac_f32_e32 v16, v83, v43
	v_fmac_f32_e32 v17, v83, v47
	v_fmac_f32_e32 v18, v83, v51
	v_fmac_f32_e32 v19, v83, v55
	v_fmac_f32_e32 v23, v83, v59
	v_lshl_add_u64 v[76:77], v[10:11], 0, s[6:7]
	global_load_dword v80, v[76:77], off
	s_add_u32 s6, s6, 0x6000
	s_addc_u32 s7, s7, 0
	v_lshl_add_u64 v[76:77], v[10:11], 0, s[6:7]
	global_load_dword v81, v[76:77], off
	s_add_u32 s6, s6, 0x6000
	s_addc_u32 s7, s7, 0
	v_lshl_add_u64 v[76:77], v[10:11], 0, s[6:7]
	global_load_dword v82, v[76:77], off
	s_add_u32 s6, s6, 0x6000
	s_addc_u32 s7, s7, 0
	v_lshl_add_u64 v[76:77], v[10:11], 0, s[6:7]
	global_load_dword v83, v[76:77], off
	s_add_u32 s6, s6, 0x6000
	s_addc_u32 s7, s7, 0
	ds_read_b128 v[24:27], v22 offset:32
	ds_read_b128 v[28:31], v22 offset:4128
	ds_read_b128 v[32:35], v22 offset:8224
	ds_read_b128 v[36:39], v22 offset:12320
	ds_read_b128 v[40:43], v22 offset:16416
	ds_read_b128 v[44:47], v22 offset:20512
	ds_read_b128 v[48:51], v22 offset:24608
	ds_read_b128 v[52:55], v22 offset:28704
	ds_read_b128 v[56:59], v22 offset:32800
	s_waitcnt vmcnt(28) lgkmcnt(9)
	v_fmac_f32_e32 v12, v84, v144
	v_fmac_f32_e32 v13, v84, v148
	v_fmac_f32_e32 v14, v84, v152
	v_fmac_f32_e32 v15, v84, v156
	v_fmac_f32_e32 v16, v84, v160
	v_fmac_f32_e32 v17, v84, v164
	v_fmac_f32_e32 v18, v84, v168
	v_fmac_f32_e32 v19, v84, v172
	v_fmac_f32_e32 v23, v84, v176
	v_fmac_f32_e32 v12, v85, v145
	v_fmac_f32_e32 v13, v85, v149
	v_fmac_f32_e32 v14, v85, v153
	v_fmac_f32_e32 v15, v85, v157
	v_fmac_f32_e32 v16, v85, v161
	v_fmac_f32_e32 v17, v85, v165
	v_fmac_f32_e32 v18, v85, v169
	v_fmac_f32_e32 v19, v85, v173
	v_fmac_f32_e32 v23, v85, v177
	v_fmac_f32_e32 v12, v86, v146
	v_fmac_f32_e32 v13, v86, v150
	v_fmac_f32_e32 v14, v86, v154
	v_fmac_f32_e32 v15, v86, v158
	v_fmac_f32_e32 v16, v86, v162
	v_fmac_f32_e32 v17, v86, v166
	v_fmac_f32_e32 v18, v86, v170
	v_fmac_f32_e32 v19, v86, v174
	v_fmac_f32_e32 v23, v86, v178
	v_fmac_f32_e32 v12, v87, v147
	v_fmac_f32_e32 v13, v87, v151
	v_fmac_f32_e32 v14, v87, v155
	v_fmac_f32_e32 v15, v87, v159
	v_fmac_f32_e32 v16, v87, v163
	v_fmac_f32_e32 v17, v87, v167
	v_fmac_f32_e32 v18, v87, v171
	v_fmac_f32_e32 v19, v87, v175
	v_fmac_f32_e32 v23, v87, v179
	v_lshl_add_u64 v[76:77], v[10:11], 0, s[6:7]
	global_load_dword v84, v[76:77], off
	s_add_u32 s6, s6, 0x6000
	s_addc_u32 s7, s7, 0
	v_lshl_add_u64 v[76:77], v[10:11], 0, s[6:7]
	global_load_dword v85, v[76:77], off
	s_add_u32 s6, s6, 0x6000
	s_addc_u32 s7, s7, 0
	v_lshl_add_u64 v[76:77], v[10:11], 0, s[6:7]
	global_load_dword v86, v[76:77], off
	s_add_u32 s6, s6, 0x6000
	s_addc_u32 s7, s7, 0
	v_lshl_add_u64 v[76:77], v[10:11], 0, s[6:7]
	global_load_dword v87, v[76:77], off
	s_add_u32 s6, s6, 0x6000
	s_addc_u32 s7, s7, 0
	ds_read_b128 v[144:147], v22 offset:48
	ds_read_b128 v[148:151], v22 offset:4144
	ds_read_b128 v[152:155], v22 offset:8240
	ds_read_b128 v[156:159], v22 offset:12336
	ds_read_b128 v[160:163], v22 offset:16432
	ds_read_b128 v[164:167], v22 offset:20528
	ds_read_b128 v[168:171], v22 offset:24624
	ds_read_b128 v[172:175], v22 offset:28720
	ds_read_b128 v[176:179], v22 offset:32816
	s_waitcnt vmcnt(28) lgkmcnt(9)
	v_fmac_f32_e32 v12, v88, v24
	v_fmac_f32_e32 v13, v88, v28
	v_fmac_f32_e32 v14, v88, v32
	v_fmac_f32_e32 v15, v88, v36
	v_fmac_f32_e32 v16, v88, v40
	v_fmac_f32_e32 v17, v88, v44
	v_fmac_f32_e32 v18, v88, v48
	v_fmac_f32_e32 v19, v88, v52
	v_fmac_f32_e32 v23, v88, v56
	v_fmac_f32_e32 v12, v89, v25
	v_fmac_f32_e32 v13, v89, v29
	v_fmac_f32_e32 v14, v89, v33
	v_fmac_f32_e32 v15, v89, v37
	v_fmac_f32_e32 v16, v89, v41
	v_fmac_f32_e32 v17, v89, v45
	v_fmac_f32_e32 v18, v89, v49
	v_fmac_f32_e32 v19, v89, v53
	v_fmac_f32_e32 v23, v89, v57
	v_fmac_f32_e32 v12, v90, v26
	v_fmac_f32_e32 v13, v90, v30
	v_fmac_f32_e32 v14, v90, v34
	v_fmac_f32_e32 v15, v90, v38
	v_fmac_f32_e32 v16, v90, v42
	v_fmac_f32_e32 v17, v90, v46
	v_fmac_f32_e32 v18, v90, v50
	v_fmac_f32_e32 v19, v90, v54
	v_fmac_f32_e32 v23, v90, v58
	v_fmac_f32_e32 v12, v91, v27
	v_fmac_f32_e32 v13, v91, v31
	v_fmac_f32_e32 v14, v91, v35
	v_fmac_f32_e32 v15, v91, v39
	v_fmac_f32_e32 v16, v91, v43
	v_fmac_f32_e32 v17, v91, v47
	v_fmac_f32_e32 v18, v91, v51
	v_fmac_f32_e32 v19, v91, v55
	v_fmac_f32_e32 v23, v91, v59
	v_lshl_add_u64 v[76:77], v[10:11], 0, s[6:7]
	global_load_dword v88, v[76:77], off
	s_add_u32 s6, s6, 0x6000
	s_addc_u32 s7, s7, 0
	v_lshl_add_u64 v[76:77], v[10:11], 0, s[6:7]
	global_load_dword v89, v[76:77], off
	s_add_u32 s6, s6, 0x6000
	s_addc_u32 s7, s7, 0
	v_lshl_add_u64 v[76:77], v[10:11], 0, s[6:7]
	global_load_dword v90, v[76:77], off
	s_add_u32 s6, s6, 0x6000
	s_addc_u32 s7, s7, 0
	v_lshl_add_u64 v[76:77], v[10:11], 0, s[6:7]
	global_load_dword v91, v[76:77], off
	s_add_u32 s6, s6, 0x6000
	s_addc_u32 s7, s7, 0
	ds_read_b128 v[24:27], v22 offset:64
	ds_read_b128 v[28:31], v22 offset:4160
	ds_read_b128 v[32:35], v22 offset:8256
	ds_read_b128 v[36:39], v22 offset:12352
	ds_read_b128 v[40:43], v22 offset:16448
	ds_read_b128 v[44:47], v22 offset:20544
	ds_read_b128 v[48:51], v22 offset:24640
	ds_read_b128 v[52:55], v22 offset:28736
	ds_read_b128 v[56:59], v22 offset:32832
	s_waitcnt vmcnt(28) lgkmcnt(9)
; DEV void ph_ada(const P& p, char* smem) {
;     ...
;       for (int k = kq * 256; k < kq * 256 + 256; ++k) {
;         const float wv = w[(size_t)k * 6144];
; #pragma unroll
;         for (int b = 0; b < 9; ++b) acc[b] += sc[b * 1024 + k] * wv;
;       }
	v_fmac_f32_e32 v12, v92, v144
	v_fmac_f32_e32 v13, v92, v148
	v_fmac_f32_e32 v14, v92, v152
	v_fmac_f32_e32 v15, v92, v156
	v_fmac_f32_e32 v16, v92, v160
	v_fmac_f32_e32 v17, v92, v164
	v_fmac_f32_e32 v18, v92, v168
	v_fmac_f32_e32 v19, v92, v172
	v_fmac_f32_e32 v23, v92, v176
	v_fmac_f32_e32 v12, v93, v145
	v_fmac_f32_e32 v13, v93, v149
	v_fmac_f32_e32 v14, v93, v153
	v_fmac_f32_e32 v15, v93, v157
	v_fmac_f32_e32 v16, v93, v161
	v_fmac_f32_e32 v17, v93, v165
	v_fmac_f32_e32 v18, v93, v169
	v_fmac_f32_e32 v19, v93, v173
	v_fmac_f32_e32 v23, v93, v177
	v_fmac_f32_e32 v12, v94, v146
	v_fmac_f32_e32 v13, v94, v150
	v_fmac_f32_e32 v14, v94, v154
	v_fmac_f32_e32 v15, v94, v158
	v_fmac_f32_e32 v16, v94, v162
	v_fmac_f32_e32 v17, v94, v166
	v_fmac_f32_e32 v18, v94, v170
	v_fmac_f32_e32 v19, v94, v174
	v_fmac_f32_e32 v23, v94, v178
	v_fmac_f32_e32 v12, v95, v147
	v_fmac_f32_e32 v13, v95, v151
	v_fmac_f32_e32 v14, v95, v155
	v_fmac_f32_e32 v15, v95, v159
	v_fmac_f32_e32 v16, v95, v163
	v_fmac_f32_e32 v17, v95, v167
	v_fmac_f32_e32 v18, v95, v171
	v_fmac_f32_e32 v19, v95, v175
	v_fmac_f32_e32 v23, v95, v179
	v_lshl_add_u64 v[76:77], v[10:11], 0, s[6:7]
	global_load_dword v92, v[76:77], off
	s_add_u32 s6, s6, 0x6000
	s_addc_u32 s7, s7, 0
	v_lshl_add_u64 v[76:77], v[10:11], 0, s[6:7]
	global_load_dword v93, v[76:77], off
	s_add_u32 s6, s6, 0x6000
	s_addc_u32 s7, s7, 0
	v_lshl_add_u64 v[76:77], v[10:11], 0, s[6:7]
	global_load_dword v94, v[76:77], off
	s_add_u32 s6, s6, 0x6000
	s_addc_u32 s7, s7, 0
	v_lshl_add_u64 v[76:77], v[10:11], 0, s[6:7]
	global_load_dword v95, v[76:77], off
	s_add_u32 s6, s6, 0x6000
	s_addc_u32 s7, s7, 0
	ds_read_b128 v[144:147], v22 offset:80
	ds_read_b128 v[148:151], v22 offset:4176
	ds_read_b128 v[152:155], v22 offset:8272
	ds_read_b128 v[156:159], v22 offset:12368
	ds_read_b128 v[160:163], v22 offset:16464
	ds_read_b128 v[164:167], v22 offset:20560
	ds_read_b128 v[168:171], v22 offset:24656
	ds_read_b128 v[172:175], v22 offset:28752
	ds_read_b128 v[176:179], v22 offset:32848
	s_waitcnt vmcnt(28) lgkmcnt(9)
	v_fmac_f32_e32 v12, v96, v24
	v_fmac_f32_e32 v13, v96, v28
	v_fmac_f32_e32 v14, v96, v32
	v_fmac_f32_e32 v15, v96, v36
	v_fmac_f32_e32 v16, v96, v40
	v_fmac_f32_e32 v17, v96, v44
	v_fmac_f32_e32 v18, v96, v48
	v_fmac_f32_e32 v19, v96, v52
	v_fmac_f32_e32 v23, v96, v56
	v_fmac_f32_e32 v12, v97, v25
	v_fmac_f32_e32 v13, v97, v29
	v_fmac_f32_e32 v14, v97, v33
	v_fmac_f32_e32 v15, v97, v37
	v_fmac_f32_e32 v16, v97, v41
	v_fmac_f32_e32 v17, v97, v45
	v_fmac_f32_e32 v18, v97, v49
	v_fmac_f32_e32 v19, v97, v53
	v_fmac_f32_e32 v23, v97, v57
	v_fmac_f32_e32 v12, v98, v26
	v_fmac_f32_e32 v13, v98, v30
	v_fmac_f32_e32 v14, v98, v34
	v_fmac_f32_e32 v15, v98, v38
	v_fmac_f32_e32 v16, v98, v42
	v_fmac_f32_e32 v17, v98, v46
	v_fmac_f32_e32 v18, v98, v50
	v_fmac_f32_e32 v19, v98, v54
	v_fmac_f32_e32 v23, v98, v58
	v_fmac_f32_e32 v12, v99, v27
	v_fmac_f32_e32 v13, v99, v31
	v_fmac_f32_e32 v14, v99, v35
	v_fmac_f32_e32 v15, v99, v39
	v_fmac_f32_e32 v16, v99, v43
	v_fmac_f32_e32 v17, v99, v47
	v_fmac_f32_e32 v18, v99, v51
	v_fmac_f32_e32 v19, v99, v55
	v_fmac_f32_e32 v23, v99, v59
	v_lshl_add_u64 v[76:77], v[10:11], 0, s[6:7]
	global_load_dword v96, v[76:77], off
	s_add_u32 s6, s6, 0x6000
	s_addc_u32 s7, s7, 0
	v_lshl_add_u64 v[76:77], v[10:11], 0, s[6:7]
	global_load_dword v97, v[76:77], off
	s_add_u32 s6, s6, 0x6000
	s_addc_u32 s7, s7, 0
	v_lshl_add_u64 v[76:77], v[10:11], 0, s[6:7]
	global_load_dword v98, v[76:77], off
	s_add_u32 s6, s6, 0x6000
	s_addc_u32 s7, s7, 0
	v_lshl_add_u64 v[76:77], v[10:11], 0, s[6:7]
	global_load_dword v99, v[76:77], off
	s_add_u32 s6, s6, 0x6000
	s_addc_u32 s7, s7, 0
	ds_read_b128 v[24:27], v22 offset:96
	ds_read_b128 v[28:31], v22 offset:4192
	ds_read_b128 v[32:35], v22 offset:8288
	ds_read_b128 v[36:39], v22 offset:12384
	ds_read_b128 v[40:43], v22 offset:16480
	ds_read_b128 v[44:47], v22 offset:20576
	ds_read_b128 v[48:51], v22 offset:24672
	ds_read_b128 v[52:55], v22 offset:28768
	ds_read_b128 v[56:59], v22 offset:32864
	s_waitcnt vmcnt(28) lgkmcnt(9)
	v_fmac_f32_e32 v12, v100, v144
	v_fmac_f32_e32 v13, v100, v148
	v_fmac_f32_e32 v14, v100, v152
	v_fmac_f32_e32 v15, v100, v156
	v_fmac_f32_e32 v16, v100, v160
	v_fmac_f32_e32 v17, v100, v164
	v_fmac_f32_e32 v18, v100, v168
	v_fmac_f32_e32 v19, v100, v172
	v_fmac_f32_e32 v23, v100, v176
	v_fmac_f32_e32 v12, v101, v145
	v_fmac_f32_e32 v13, v101, v149
	v_fmac_f32_e32 v14, v101, v153
	v_fmac_f32_e32 v15, v101, v157
	v_fmac_f32_e32 v16, v101, v161
	v_fmac_f32_e32 v17, v101, v165
	v_fmac_f32_e32 v18, v101, v169
	v_fmac_f32_e32 v19, v101, v173
	v_fmac_f32_e32 v23, v101, v177
	v_fmac_f32_e32 v12, v102, v146
	v_fmac_f32_e32 v13, v102, v150
	v_fmac_f32_e32 v14, v102, v154
	v_fmac_f32_e32 v15, v102, v158
	v_fmac_f32_e32 v16, v102, v162
	v_fmac_f32_e32 v17, v102, v166
	v_fmac_f32_e32 v18, v102, v170
	v_fmac_f32_e32 v19, v102, v174
	v_fmac_f32_e32 v23, v102, v178
	v_fmac_f32_e32 v12, v103, v147
	v_fmac_f32_e32 v13, v103, v151
	v_fmac_f32_e32 v14, v103, v155
	v_fmac_f32_e32 v15, v103, v159
	v_fmac_f32_e32 v16, v103, v163
	v_fmac_f32_e32 v17, v103, v167
	v_fmac_f32_e32 v18, v103, v171
	v_fmac_f32_e32 v19, v103, v175
	v_fmac_f32_e32 v23, v103, v179
	v_lshl_add_u64 v[76:77], v[10:11], 0, s[6:7]
	global_load_dword v100, v[76:77], off
	s_add_u32 s6, s6, 0x6000
	s_addc_u32 s7, s7, 0
	v_lshl_add_u64 v[76:77], v[10:11], 0, s[6:7]
	global_load_dword v101, v[76:77], off
	s_add_u32 s6, s6, 0x6000
	s_addc_u32 s7, s7, 0
	v_lshl_add_u64 v[76:77], v[10:11], 0, s[6:7]
	global_load_dword v102, v[76:77], off
	s_add_u32 s6, s6, 0x6000
	s_addc_u32 s7, s7, 0
	v_lshl_add_u64 v[76:77], v[10:11], 0, s[6:7]
	global_load_dword v103, v[76:77], off
	s_add_u32 s6, s6, 0x6000
	s_addc_u32 s7, s7, 0
	ds_read_b128 v[144:147], v22 offset:112
	ds_read_b128 v[148:151], v22 offset:4208
	ds_read_b128 v[152:155], v22 offset:8304
	ds_read_b128 v[156:159], v22 offset:12400
	ds_read_b128 v[160:163], v22 offset:16496
	ds_read_b128 v[164:167], v22 offset:20592
	ds_read_b128 v[168:171], v22 offset:24688
	ds_read_b128 v[172:175], v22 offset:28784
	ds_read_b128 v[176:179], v22 offset:32880
	s_waitcnt vmcnt(28) lgkmcnt(9)
; DEV void ph_ada(const P& p, char* smem) {
;     ...
;       for (int k = kq * 256; k < kq * 256 + 256; ++k) {
;         const float wv = w[(size_t)k * 6144];
; #pragma unroll
;         for (int b = 0; b < 9; ++b) acc[b] += sc[b * 1024 + k] * wv;
;       }
	v_fmac_f32_e32 v12, v104, v24
	v_fmac_f32_e32 v13, v104, v28
	v_fmac_f32_e32 v14, v104, v32
	v_fmac_f32_e32 v15, v104, v36
	v_fmac_f32_e32 v16, v104, v40
	v_fmac_f32_e32 v17, v104, v44
	v_fmac_f32_e32 v18, v104, v48
	v_fmac_f32_e32 v19, v104, v52
	v_fmac_f32_e32 v23, v104, v56
	v_fmac_f32_e32 v12, v105, v25
	v_fmac_f32_e32 v13, v105, v29
	v_fmac_f32_e32 v14, v105, v33
	v_fmac_f32_e32 v15, v105, v37
	v_fmac_f32_e32 v16, v105, v41
	v_fmac_f32_e32 v17, v105, v45
	v_fmac_f32_e32 v18, v105, v49
	v_fmac_f32_e32 v19, v105, v53
	v_fmac_f32_e32 v23, v105, v57
	v_fmac_f32_e32 v12, v106, v26
	v_fmac_f32_e32 v13, v106, v30
	v_fmac_f32_e32 v14, v106, v34
	v_fmac_f32_e32 v15, v106, v38
	v_fmac_f32_e32 v16, v106, v42
	v_fmac_f32_e32 v17, v106, v46
	v_fmac_f32_e32 v18, v106, v50
	v_fmac_f32_e32 v19, v106, v54
	v_fmac_f32_e32 v23, v106, v58
	v_fmac_f32_e32 v12, v107, v27
	v_fmac_f32_e32 v13, v107, v31
	v_fmac_f32_e32 v14, v107, v35
	v_fmac_f32_e32 v15, v107, v39
	v_fmac_f32_e32 v16, v107, v43
	v_fmac_f32_e32 v17, v107, v47
	v_fmac_f32_e32 v18, v107, v51
	v_fmac_f32_e32 v19, v107, v55
	v_fmac_f32_e32 v23, v107, v59
	v_lshl_add_u64 v[76:77], v[10:11], 0, s[6:7]
	global_load_dword v104, v[76:77], off
	s_add_u32 s6, s6, 0x6000
	s_addc_u32 s7, s7, 0
	v_lshl_add_u64 v[76:77], v[10:11], 0, s[6:7]
	global_load_dword v105, v[76:77], off
	s_add_u32 s6, s6, 0x6000
	s_addc_u32 s7, s7, 0
	v_lshl_add_u64 v[76:77], v[10:11], 0, s[6:7]
	global_load_dword v106, v[76:77], off
	s_add_u32 s6, s6, 0x6000
	s_addc_u32 s7, s7, 0
	v_lshl_add_u64 v[76:77], v[10:11], 0, s[6:7]
	global_load_dword v107, v[76:77], off
	s_add_u32 s6, s6, 0x6000
	s_addc_u32 s7, s7, 0
	ds_read_b128 v[24:27], v22 offset:128
	ds_read_b128 v[28:31], v22 offset:4224
	ds_read_b128 v[32:35], v22 offset:8320
	ds_read_b128 v[36:39], v22 offset:12416
	ds_read_b128 v[40:43], v22 offset:16512
	ds_read_b128 v[44:47], v22 offset:20608
	ds_read_b128 v[48:51], v22 offset:24704
	ds_read_b128 v[52:55], v22 offset:28800
	ds_read_b128 v[56:59], v22 offset:32896
	s_waitcnt vmcnt(28) lgkmcnt(9)
	v_fmac_f32_e32 v12, v108, v144
	v_fmac_f32_e32 v13, v108, v148
	v_fmac_f32_e32 v14, v108, v152
	v_fmac_f32_e32 v15, v108, v156
	v_fmac_f32_e32 v16, v108, v160
	v_fmac_f32_e32 v17, v108, v164
	v_fmac_f32_e32 v18, v108, v168
	v_fmac_f32_e32 v19, v108, v172
	v_fmac_f32_e32 v23, v108, v176
	v_fmac_f32_e32 v12, v109, v145
	v_fmac_f32_e32 v13, v109, v149
	v_fmac_f32_e32 v14, v109, v153
	v_fmac_f32_e32 v15, v109, v157
	v_fmac_f32_e32 v16, v109, v161
	v_fmac_f32_e32 v17, v109, v165
	v_fmac_f32_e32 v18, v109, v169
	v_fmac_f32_e32 v19, v109, v173
	v_fmac_f32_e32 v23, v109, v177
	v_fmac_f32_e32 v12, v110, v146
	v_fmac_f32_e32 v13, v110, v150
	v_fmac_f32_e32 v14, v110, v154
	v_fmac_f32_e32 v15, v110, v158
	v_fmac_f32_e32 v16, v110, v162
	v_fmac_f32_e32 v17, v110, v166
	v_fmac_f32_e32 v18, v110, v170
	v_fmac_f32_e32 v19, v110, v174
	v_fmac_f32_e32 v23, v110, v178
	v_fmac_f32_e32 v12, v111, v147
	v_fmac_f32_e32 v13, v111, v151
	v_fmac_f32_e32 v14, v111, v155
	v_fmac_f32_e32 v15, v111, v159
	v_fmac_f32_e32 v16, v111, v163
	v_fmac_f32_e32 v17, v111, v167
	v_fmac_f32_e32 v18, v111, v171
	v_fmac_f32_e32 v19, v111, v175
	v_fmac_f32_e32 v23, v111, v179
	v_lshl_add_u64 v[76:77], v[10:11], 0, s[6:7]
	global_load_dword v108, v[76:77], off
	s_add_u32 s6, s6, 0x6000
	s_addc_u32 s7, s7, 0
	v_lshl_add_u64 v[76:77], v[10:11], 0, s[6:7]
	global_load_dword v109, v[76:77], off
	s_add_u32 s6, s6, 0x6000
	s_addc_u32 s7, s7, 0
	v_lshl_add_u64 v[76:77], v[10:11], 0, s[6:7]
	global_load_dword v110, v[76:77], off
	s_add_u32 s6, s6, 0x6000
	s_addc_u32 s7, s7, 0
	v_lshl_add_u64 v[76:77], v[10:11], 0, s[6:7]
	global_load_dword v111, v[76:77], off
	s_add_u32 s6, s6, 0x6000
	s_addc_u32 s7, s7, 0
	v_add_u32_e32 v22, 0x80, v22
	s_sub_i32 s4, s4, 1
	s_cmp_lg_u32 s4, 0
	s_cbranch_scc1 .Lada_loop
	ds_read_b128 v[144:147], v22 offset:16
	ds_read_b128 v[148:151], v22 offset:4112
	ds_read_b128 v[152:155], v22 offset:8208
	ds_read_b128 v[156:159], v22 offset:12304
	ds_read_b128 v[160:163], v22 offset:16400
	ds_read_b128 v[164:167], v22 offset:20496
	ds_read_b128 v[168:171], v22 offset:24592
	ds_read_b128 v[172:175], v22 offset:28688
	ds_read_b128 v[176:179], v22 offset:32784
	s_waitcnt vmcnt(28) lgkmcnt(9)
	v_fmac_f32_e32 v12, v80, v24
	v_fmac_f32_e32 v13, v80, v28
	v_fmac_f32_e32 v14, v80, v32
	v_fmac_f32_e32 v15, v80, v36
	v_fmac_f32_e32 v16, v80, v40
	v_fmac_f32_e32 v17, v80, v44
	v_fmac_f32_e32 v18, v80, v48
	v_fmac_f32_e32 v19, v80, v52
	v_fmac_f32_e32 v23, v80, v56
	v_fmac_f32_e32 v12, v81, v25
	v_fmac_f32_e32 v13, v81, v29
	v_fmac_f32_e32 v14, v81, v33
	v_fmac_f32_e32 v15, v81, v37
	v_fmac_f32_e32 v16, v81, v41
	v_fmac_f32_e32 v17, v81, v45
	v_fmac_f32_e32 v18, v81, v49
	v_fmac_f32_e32 v19, v81, v53
	v_fmac_f32_e32 v23, v81, v57
	v_fmac_f32_e32 v12, v82, v26
	v_fmac_f32_e32 v13, v82, v30
	v_fmac_f32_e32 v14, v82, v34
	v_fmac_f32_e32 v15, v82, v38
	v_fmac_f32_e32 v16, v82, v42
	v_fmac_f32_e32 v17, v82, v46
	v_fmac_f32_e32 v18, v82, v50
	v_fmac_f32_e32 v19, v82, v54
	v_fmac_f32_e32 v23, v82, v58
	v_fmac_f32_e32 v12, v83, v27
	v_fmac_f32_e32 v13, v83, v31
	v_fmac_f32_e32 v14, v83, v35
	v_fmac_f32_e32 v15, v83, v39
	v_fmac_f32_e32 v16, v83, v43
	v_fmac_f32_e32 v17, v83, v47
	v_fmac_f32_e32 v18, v83, v51
	v_fmac_f32_e32 v19, v83, v55
	v_fmac_f32_e32 v23, v83, v59
	ds_read_b128 v[24:27], v22 offset:32
	ds_read_b128 v[28:31], v22 offset:4128
	ds_read_b128 v[32:35], v22 offset:8224
	ds_read_b128 v[36:39], v22 offset:12320
	ds_read_b128 v[40:43], v22 offset:16416
	ds_read_b128 v[44:47], v22 offset:20512
	ds_read_b128 v[48:51], v22 offset:24608
	ds_read_b128 v[52:55], v22 offset:28704
	ds_read_b128 v[56:59], v22 offset:32800
	s_waitcnt vmcnt(24) lgkmcnt(9)
; DEV void ph_ada(const P& p, char* smem) {
;     ...
;       for (int k = kq * 256; k < kq * 256 + 256; ++k) {
;         const float wv = w[(size_t)k * 6144];
; #pragma unroll
;         for (int b = 0; b < 9; ++b) acc[b] += sc[b * 1024 + k] * wv;
;       }
	v_fmac_f32_e32 v12, v84, v144
	v_fmac_f32_e32 v13, v84, v148
	v_fmac_f32_e32 v14, v84, v152
	v_fmac_f32_e32 v15, v84, v156
	v_fmac_f32_e32 v16, v84, v160
	v_fmac_f32_e32 v17, v84, v164
	v_fmac_f32_e32 v18, v84, v168
	v_fmac_f32_e32 v19, v84, v172
	v_fmac_f32_e32 v23, v84, v176
	v_fmac_f32_e32 v12, v85, v145
	v_fmac_f32_e32 v13, v85, v149
	v_fmac_f32_e32 v14, v85, v153
	v_fmac_f32_e32 v15, v85, v157
	v_fmac_f32_e32 v16, v85, v161
	v_fmac_f32_e32 v17, v85, v165
	v_fmac_f32_e32 v18, v85, v169
	v_fmac_f32_e32 v19, v85, v173
	v_fmac_f32_e32 v23, v85, v177
	v_fmac_f32_e32 v12, v86, v146
	v_fmac_f32_e32 v13, v86, v150
	v_fmac_f32_e32 v14, v86, v154
	v_fmac_f32_e32 v15, v86, v158
	v_fmac_f32_e32 v16, v86, v162
	v_fmac_f32_e32 v17, v86, v166
	v_fmac_f32_e32 v18, v86, v170
	v_fmac_f32_e32 v19, v86, v174
	v_fmac_f32_e32 v23, v86, v178
	v_fmac_f32_e32 v12, v87, v147
	v_fmac_f32_e32 v13, v87, v151
	v_fmac_f32_e32 v14, v87, v155
	v_fmac_f32_e32 v15, v87, v159
	v_fmac_f32_e32 v16, v87, v163
	v_fmac_f32_e32 v17, v87, v167
	v_fmac_f32_e32 v18, v87, v171
	v_fmac_f32_e32 v19, v87, v175
	v_fmac_f32_e32 v23, v87, v179
	ds_read_b128 v[144:147], v22 offset:48
	ds_read_b128 v[148:151], v22 offset:4144
	ds_read_b128 v[152:155], v22 offset:8240
	ds_read_b128 v[156:159], v22 offset:12336
	ds_read_b128 v[160:163], v22 offset:16432
	ds_read_b128 v[164:167], v22 offset:20528
	ds_read_b128 v[168:171], v22 offset:24624
	ds_read_b128 v[172:175], v22 offset:28720
	ds_read_b128 v[176:179], v22 offset:32816
	s_waitcnt vmcnt(20) lgkmcnt(9)
	v_fmac_f32_e32 v12, v88, v24
	v_fmac_f32_e32 v13, v88, v28
	v_fmac_f32_e32 v14, v88, v32
	v_fmac_f32_e32 v15, v88, v36
	v_fmac_f32_e32 v16, v88, v40
	v_fmac_f32_e32 v17, v88, v44
	v_fmac_f32_e32 v18, v88, v48
	v_fmac_f32_e32 v19, v88, v52
	v_fmac_f32_e32 v23, v88, v56
	v_fmac_f32_e32 v12, v89, v25
	v_fmac_f32_e32 v13, v89, v29
	v_fmac_f32_e32 v14, v89, v33
	v_fmac_f32_e32 v15, v89, v37
	v_fmac_f32_e32 v16, v89, v41
	v_fmac_f32_e32 v17, v89, v45
	v_fmac_f32_e32 v18, v89, v49
	v_fmac_f32_e32 v19, v89, v53
	v_fmac_f32_e32 v23, v89, v57
	v_fmac_f32_e32 v12, v90, v26
	v_fmac_f32_e32 v13, v90, v30
	v_fmac_f32_e32 v14, v90, v34
	v_fmac_f32_e32 v15, v90, v38
	v_fmac_f32_e32 v16, v90, v42
	v_fmac_f32_e32 v17, v90, v46
	v_fmac_f32_e32 v18, v90, v50
	v_fmac_f32_e32 v19, v90, v54
	v_fmac_f32_e32 v23, v90, v58
	v_fmac_f32_e32 v12, v91, v27
	v_fmac_f32_e32 v13, v91, v31
	v_fmac_f32_e32 v14, v91, v35
	v_fmac_f32_e32 v15, v91, v39
	v_fmac_f32_e32 v16, v91, v43
	v_fmac_f32_e32 v17, v91, v47
	v_fmac_f32_e32 v18, v91, v51
	v_fmac_f32_e32 v19, v91, v55
	v_fmac_f32_e32 v23, v91, v59
	ds_read_b128 v[24:27], v22 offset:64
	ds_read_b128 v[28:31], v22 offset:4160
	ds_read_b128 v[32:35], v22 offset:8256
	ds_read_b128 v[36:39], v22 offset:12352
	ds_read_b128 v[40:43], v22 offset:16448
	ds_read_b128 v[44:47], v22 offset:20544
	ds_read_b128 v[48:51], v22 offset:24640
	ds_read_b128 v[52:55], v22 offset:28736
	ds_read_b128 v[56:59], v22 offset:32832
	s_waitcnt vmcnt(16) lgkmcnt(9)
	v_fmac_f32_e32 v12, v92, v144
	v_fmac_f32_e32 v13, v92, v148
	v_fmac_f32_e32 v14, v92, v152
	v_fmac_f32_e32 v15, v92, v156
	v_fmac_f32_e32 v16, v92, v160
	v_fmac_f32_e32 v17, v92, v164
	v_fmac_f32_e32 v18, v92, v168
	v_fmac_f32_e32 v19, v92, v172
	v_fmac_f32_e32 v23, v92, v176
	v_fmac_f32_e32 v12, v93, v145
	v_fmac_f32_e32 v13, v93, v149
	v_fmac_f32_e32 v14, v93, v153
	v_fmac_f32_e32 v15, v93, v157
	v_fmac_f32_e32 v16, v93, v161
	v_fmac_f32_e32 v17, v93, v165
	v_fmac_f32_e32 v18, v93, v169
	v_fmac_f32_e32 v19, v93, v173
	v_fmac_f32_e32 v23, v93, v177
	v_fmac_f32_e32 v12, v94, v146
	v_fmac_f32_e32 v13, v94, v150
	v_fmac_f32_e32 v14, v94, v154
	v_fmac_f32_e32 v15, v94, v158
	v_fmac_f32_e32 v16, v94, v162
	v_fmac_f32_e32 v17, v94, v166
	v_fmac_f32_e32 v18, v94, v170
	v_fmac_f32_e32 v19, v94, v174
	v_fmac_f32_e32 v23, v94, v178
	v_fmac_f32_e32 v12, v95, v147
	v_fmac_f32_e32 v13, v95, v151
	v_fmac_f32_e32 v14, v95, v155
	v_fmac_f32_e32 v15, v95, v159
	v_fmac_f32_e32 v16, v95, v163
	v_fmac_f32_e32 v17, v95, v167
	v_fmac_f32_e32 v18, v95, v171
	v_fmac_f32_e32 v19, v95, v175
	v_fmac_f32_e32 v23, v95, v179
	ds_read_b128 v[144:147], v22 offset:80
	ds_read_b128 v[148:151], v22 offset:4176
	ds_read_b128 v[152:155], v22 offset:8272
	ds_read_b128 v[156:159], v22 offset:12368
	ds_read_b128 v[160:163], v22 offset:16464
	ds_read_b128 v[164:167], v22 offset:20560
	ds_read_b128 v[168:171], v22 offset:24656
	ds_read_b128 v[172:175], v22 offset:28752
	ds_read_b128 v[176:179], v22 offset:32848
	s_waitcnt vmcnt(12) lgkmcnt(9)
; DEV void ph_ada(const P& p, char* smem) {
;     ...
;       for (int k = kq * 256; k < kq * 256 + 256; ++k) {
;         const float wv = w[(size_t)k * 6144];
; #pragma unroll
;         for (int b = 0; b < 9; ++b) acc[b] += sc[b * 1024 + k] * wv;
;       }
; #pragma unroll
;       for (int b = 0; b < 9; ++b) red[(kq * 9 + b) * 64 + nn] = acc[b];
;       __syncthreads();
;       for (int e = tid; e < 9 * 64; e += 256) {
;         const int b = e >> 6, n = e & 63;
;         const float v = red[(0 * 9 + b) * 64 + n] + red[(1 * 9 + b) * 64 + n] + red[(2 * 9 + b) * 64 + n] + red[(3 * 9 + b) * 64 + n];
	v_fmac_f32_e32 v12, v96, v24
	v_fmac_f32_e32 v13, v96, v28
	v_fmac_f32_e32 v14, v96, v32
	v_fmac_f32_e32 v15, v96, v36
	v_fmac_f32_e32 v16, v96, v40
	v_fmac_f32_e32 v17, v96, v44
	v_fmac_f32_e32 v18, v96, v48
	v_fmac_f32_e32 v19, v96, v52
	v_fmac_f32_e32 v23, v96, v56
	v_fmac_f32_e32 v12, v97, v25
	v_fmac_f32_e32 v13, v97, v29
	v_fmac_f32_e32 v14, v97, v33
	v_fmac_f32_e32 v15, v97, v37
	v_fmac_f32_e32 v16, v97, v41
	v_fmac_f32_e32 v17, v97, v45
	v_fmac_f32_e32 v18, v97, v49
	v_fmac_f32_e32 v19, v97, v53
	v_fmac_f32_e32 v23, v97, v57
	v_fmac_f32_e32 v12, v98, v26
	v_fmac_f32_e32 v13, v98, v30
	v_fmac_f32_e32 v14, v98, v34
	v_fmac_f32_e32 v15, v98, v38
	v_fmac_f32_e32 v16, v98, v42
	v_fmac_f32_e32 v17, v98, v46
	v_fmac_f32_e32 v18, v98, v50
	v_fmac_f32_e32 v19, v98, v54
	v_fmac_f32_e32 v23, v98, v58
	v_fmac_f32_e32 v12, v99, v27
	v_fmac_f32_e32 v13, v99, v31
	v_fmac_f32_e32 v14, v99, v35
	v_fmac_f32_e32 v15, v99, v39
	v_fmac_f32_e32 v16, v99, v43
	v_fmac_f32_e32 v17, v99, v47
	v_fmac_f32_e32 v18, v99, v51
	v_fmac_f32_e32 v19, v99, v55
	v_fmac_f32_e32 v23, v99, v59
	ds_read_b128 v[24:27], v22 offset:96
	ds_read_b128 v[28:31], v22 offset:4192
	ds_read_b128 v[32:35], v22 offset:8288
	ds_read_b128 v[36:39], v22 offset:12384
	ds_read_b128 v[40:43], v22 offset:16480
	ds_read_b128 v[44:47], v22 offset:20576
	ds_read_b128 v[48:51], v22 offset:24672
	ds_read_b128 v[52:55], v22 offset:28768
	ds_read_b128 v[56:59], v22 offset:32864
	s_waitcnt vmcnt(8) lgkmcnt(9)
	v_fmac_f32_e32 v12, v100, v144
	v_fmac_f32_e32 v13, v100, v148
	v_fmac_f32_e32 v14, v100, v152
	v_fmac_f32_e32 v15, v100, v156
	v_fmac_f32_e32 v16, v100, v160
	v_fmac_f32_e32 v17, v100, v164
	v_fmac_f32_e32 v18, v100, v168
	v_fmac_f32_e32 v19, v100, v172
	v_fmac_f32_e32 v23, v100, v176
	v_fmac_f32_e32 v12, v101, v145
	v_fmac_f32_e32 v13, v101, v149
	v_fmac_f32_e32 v14, v101, v153
	v_fmac_f32_e32 v15, v101, v157
	v_fmac_f32_e32 v16, v101, v161
	v_fmac_f32_e32 v17, v101, v165
	v_fmac_f32_e32 v18, v101, v169
	v_fmac_f32_e32 v19, v101, v173
	v_fmac_f32_e32 v23, v101, v177
	v_fmac_f32_e32 v12, v102, v146
	v_fmac_f32_e32 v13, v102, v150
	v_fmac_f32_e32 v14, v102, v154
	v_fmac_f32_e32 v15, v102, v158
	v_fmac_f32_e32 v16, v102, v162
	v_fmac_f32_e32 v17, v102, v166
	v_fmac_f32_e32 v18, v102, v170
	v_fmac_f32_e32 v19, v102, v174
	v_fmac_f32_e32 v23, v102, v178
	v_fmac_f32_e32 v12, v103, v147
	v_fmac_f32_e32 v13, v103, v151
	v_fmac_f32_e32 v14, v103, v155
	v_fmac_f32_e32 v15, v103, v159
	v_fmac_f32_e32 v16, v103, v163
	v_fmac_f32_e32 v17, v103, v167
	v_fmac_f32_e32 v18, v103, v171
	v_fmac_f32_e32 v19, v103, v175
	v_fmac_f32_e32 v23, v103, v179
	ds_read_b128 v[144:147], v22 offset:112
	ds_read_b128 v[148:151], v22 offset:4208
	ds_read_b128 v[152:155], v22 offset:8304
	ds_read_b128 v[156:159], v22 offset:12400
	ds_read_b128 v[160:163], v22 offset:16496
	ds_read_b128 v[164:167], v22 offset:20592
	ds_read_b128 v[168:171], v22 offset:24688
	ds_read_b128 v[172:175], v22 offset:28784
	ds_read_b128 v[176:179], v22 offset:32880
	s_waitcnt vmcnt(4) lgkmcnt(9)
	v_fmac_f32_e32 v12, v104, v24
	v_fmac_f32_e32 v13, v104, v28
	v_fmac_f32_e32 v14, v104, v32
	v_fmac_f32_e32 v15, v104, v36
	v_fmac_f32_e32 v16, v104, v40
	v_fmac_f32_e32 v17, v104, v44
	v_fmac_f32_e32 v18, v104, v48
	v_fmac_f32_e32 v19, v104, v52
	v_fmac_f32_e32 v23, v104, v56
	v_fmac_f32_e32 v12, v105, v25
	v_fmac_f32_e32 v13, v105, v29
	v_fmac_f32_e32 v14, v105, v33
	v_fmac_f32_e32 v15, v105, v37
	v_fmac_f32_e32 v16, v105, v41
	v_fmac_f32_e32 v17, v105, v45
	v_fmac_f32_e32 v18, v105, v49
	v_fmac_f32_e32 v19, v105, v53
	v_fmac_f32_e32 v23, v105, v57
	v_fmac_f32_e32 v12, v106, v26
	v_fmac_f32_e32 v13, v106, v30
	v_fmac_f32_e32 v14, v106, v34
	v_fmac_f32_e32 v15, v106, v38
	v_fmac_f32_e32 v16, v106, v42
	v_fmac_f32_e32 v17, v106, v46
	v_fmac_f32_e32 v18, v106, v50
	v_fmac_f32_e32 v19, v106, v54
	v_fmac_f32_e32 v23, v106, v58
	v_fmac_f32_e32 v12, v107, v27
	v_fmac_f32_e32 v13, v107, v31
	v_fmac_f32_e32 v14, v107, v35
	v_fmac_f32_e32 v15, v107, v39
	v_fmac_f32_e32 v16, v107, v43
	v_fmac_f32_e32 v17, v107, v47
	v_fmac_f32_e32 v18, v107, v51
	v_fmac_f32_e32 v19, v107, v55
	v_fmac_f32_e32 v23, v107, v59
	s_waitcnt vmcnt(0) lgkmcnt(0)
	v_fmac_f32_e32 v12, v108, v144
	v_fmac_f32_e32 v13, v108, v148
	v_fmac_f32_e32 v14, v108, v152
	v_fmac_f32_e32 v15, v108, v156
	v_fmac_f32_e32 v16, v108, v160
	v_fmac_f32_e32 v17, v108, v164
	v_fmac_f32_e32 v18, v108, v168
	v_fmac_f32_e32 v19, v108, v172
	v_fmac_f32_e32 v23, v108, v176
	v_fmac_f32_e32 v12, v109, v145
	v_fmac_f32_e32 v13, v109, v149
	v_fmac_f32_e32 v14, v109, v153
	v_fmac_f32_e32 v15, v109, v157
	v_fmac_f32_e32 v16, v109, v161
	v_fmac_f32_e32 v17, v109, v165
	v_fmac_f32_e32 v18, v109, v169
	v_fmac_f32_e32 v19, v109, v173
	v_fmac_f32_e32 v23, v109, v177
	v_fmac_f32_e32 v12, v110, v146
	v_fmac_f32_e32 v13, v110, v150
	v_fmac_f32_e32 v14, v110, v154
	v_fmac_f32_e32 v15, v110, v158
	v_fmac_f32_e32 v16, v110, v162
	v_fmac_f32_e32 v17, v110, v166
	v_fmac_f32_e32 v18, v110, v170
	v_fmac_f32_e32 v19, v110, v174
	v_fmac_f32_e32 v23, v110, v178
	v_fmac_f32_e32 v12, v111, v147
	v_fmac_f32_e32 v13, v111, v151
	v_fmac_f32_e32 v14, v111, v155
	v_fmac_f32_e32 v15, v111, v159
	v_fmac_f32_e32 v16, v111, v163
	v_fmac_f32_e32 v17, v111, v167
	v_fmac_f32_e32 v18, v111, v171
	v_fmac_f32_e32 v19, v111, v175
	v_fmac_f32_e32 v23, v111, v179
	ds_write2st64_b32 v21, v12, v13 offset0:144 offset1:145
	ds_write2st64_b32 v21, v14, v15 offset0:146 offset1:147
	ds_write2st64_b32 v21, v16, v17 offset0:148 offset1:149
	ds_write2st64_b32 v21, v18, v19 offset0:150 offset1:151
	ds_write_b32 v21, v23 offset:38912
	s_waitcnt lgkmcnt(0)
	s_barrier
	s_and_saveexec_b64 s[6:7], vcc
	s_cbranch_execz .LBB0_18
	s_mul_i32 s4, s14, 0x1800
	s_add_i32 s4, s4, s2
	v_or_b32_e32 v10, s4, v1
	v_ashrrev_i32_e32 v11, 31, v10
	s_mul_hi_i32 s15, s14, 9
	s_mul_i32 s14, s14, 9
	v_lshl_add_u64 v[10:11], v[10:11], 2, s[12:13]
	v_lshl_add_u64 v[12:13], s[2:3], 2, v[6:7]
	s_mov_b64 s[2:3], 0
	v_mov_b32_e32 v14, v20
	v_mov_b32_e32 v15, v2
